# snake MFMA order inside each 8-MFMA group of the GEMM M segments (each MFMA shares one operand register with its predecessor), on top of v11
# baseline (speedup 1.0000x reference)
.Lpeel_join375_1:
	s_waitcnt lgkmcnt(0)
	s_barrier
	s_setprio 1
	s_waitcnt lgkmcnt(0)
	v_mfma_f32_16x16x32_bf16 v[120:123], v[128:131], v[178:181], 0
	v_mfma_f32_16x16x32_bf16 v[124:127], v[136:139], v[178:181], 0
	v_mfma_f32_16x16x32_bf16 v[96:99], v[136:139], v[206:209], 0
	v_mfma_f32_16x16x32_bf16 v[100:103], v[128:131], v[206:209], 0
	v_mfma_f32_16x16x32_bf16 v[84:87], v[128:131], v[214:217], 0
	v_mfma_f32_16x16x32_bf16 v[80:83], v[136:139], v[214:217], 0
	v_mfma_f32_16x16x32_bf16 v[64:67], v[136:139], v[222:225], 0
	v_mfma_f32_16x16x32_bf16 v[68:71], v[128:131], v[222:225], 0
	v_mfma_f32_16x16x32_bf16 v[120:123], v[132:135], v[202:205], v[120:123]
	v_mfma_f32_16x16x32_bf16 v[124:127], v[140:143], v[202:205], v[124:127]
	v_mfma_f32_16x16x32_bf16 v[96:99], v[140:143], v[210:213], v[96:99]
	v_mfma_f32_16x16x32_bf16 v[100:103], v[132:135], v[210:213], v[100:103]
	v_mfma_f32_16x16x32_bf16 v[84:87], v[132:135], v[218:221], v[84:87]
	v_mfma_f32_16x16x32_bf16 v[80:83], v[140:143], v[218:221], v[80:83]
	v_mfma_f32_16x16x32_bf16 v[64:67], v[140:143], v[226:229], v[64:67]
	v_mfma_f32_16x16x32_bf16 v[68:71], v[132:135], v[226:229], v[68:71]
	v_mfma_f32_16x16x32_bf16 v[116:119], v[144:147], v[178:181], 0
	v_mfma_f32_16x16x32_bf16 v[112:115], v[170:173], v[178:181], 0
	v_mfma_f32_16x16x32_bf16 v[104:107], v[170:173], v[206:209], 0
	v_mfma_f32_16x16x32_bf16 v[108:111], v[144:147], v[206:209], 0
	v_mfma_f32_16x16x32_bf16 v[92:95], v[144:147], v[214:217], 0
	v_mfma_f32_16x16x32_bf16 v[88:91], v[170:173], v[214:217], 0
	v_mfma_f32_16x16x32_bf16 v[72:75], v[170:173], v[222:225], 0
	v_mfma_f32_16x16x32_bf16 v[76:79], v[144:147], v[222:225], 0
	v_mfma_f32_16x16x32_bf16 v[116:119], v[148:151], v[202:205], v[116:119]
	v_mfma_f32_16x16x32_bf16 v[112:115], v[174:177], v[202:205], v[112:115]
	v_mfma_f32_16x16x32_bf16 v[104:107], v[174:177], v[210:213], v[104:107]
	v_mfma_f32_16x16x32_bf16 v[108:111], v[148:151], v[210:213], v[108:111]
	v_mfma_f32_16x16x32_bf16 v[92:95], v[148:151], v[218:221], v[92:95]
	v_mfma_f32_16x16x32_bf16 v[88:91], v[174:177], v[218:221], v[88:91]
	v_mfma_f32_16x16x32_bf16 v[72:75], v[174:177], v[226:229], v[72:75]
	v_mfma_f32_16x16x32_bf16 v[76:79], v[148:151], v[226:229], v[76:79]
	s_setprio 0
	s_barrier
	s_add_i32 s12, s12, s17
	v_lshl_add_u64 v[230:231], s[14:15], 0, v[154:155]
	s_mov_b32 m0, s12
	ds_read_b128 v[178:181], v157 offset:16384
	ds_read_b128 v[202:205], v157 offset:17408
	ds_read_b128 v[206:209], v157 offset:18432
	ds_read_b128 v[210:213], v157 offset:19456
	ds_read_b128 v[214:217], v157 offset:20480
	ds_read_b128 v[218:221], v157 offset:21504
	ds_read_b128 v[222:225], v157 offset:22528
	ds_read_b128 v[226:229], v157 offset:23552
	global_load_lds_dwordx4 v[230:231], off
	s_add_i32 m0, s12, 0x2000
	v_lshl_add_u64 v[232:233], s[14:15], 0, v[162:163]
	s_add_u32 s14, s14, s24
	s_addc_u32 s15, s15, s25
	s_add_i32 s2, s2, s17
	global_load_lds_dwordx4 v[232:233], off
	v_lshl_add_u64 v[234:235], s[14:15], 0, v[154:155]
	s_mov_b32 m0, s2
	v_lshl_add_u64 v[236:237], s[14:15], 0, v[162:163]
	global_load_lds_dwordx4 v[234:235], off
	s_add_i32 m0, s2, 0x2000
	v_lshl_add_u64 v[238:239], s[0:1], 0, v[158:159]
	global_load_lds_dwordx4 v[236:237], off
	s_mov_b32 m0, s45
	v_lshl_add_u64 v[240:241], s[0:1], 0, v[160:161]
	global_load_lds_dwordx4 v[238:239], off
	s_mov_b32 m0, s83
	s_nop 0
	global_load_lds_dwordx4 v[240:241], off
	s_lshl_b32 s99, s17, 1
	s_add_i32 m0, s99, 0x20000
	s_lshl_b32 s98, s65, 14
	s_add_i32 s98, s98, s99
	s_add_u32 s98, s100, s98
	s_addc_u32 s99, s101, 0
	global_load_lds_dwordx4 v248, s[98:99]
	global_load_lds_dwordx4 v248, s[98:99] offset:1024
	s_cmp_eq_u32 s18, 1
	s_cbranch_scc1 .Lpeel_strict375_2
	s_waitcnt vmcnt(18)
	s_branch .Lpeel_join375_2

.Lpeel_join375_2:
	s_waitcnt lgkmcnt(0)
	s_barrier
	s_setprio 1
	s_waitcnt lgkmcnt(0)
	v_mfma_f32_16x16x32_bf16 v[52:55], v[128:131], v[178:181], 0
	v_mfma_f32_16x16x32_bf16 v[48:51], v[136:139], v[178:181], 0
	v_mfma_f32_16x16x32_bf16 v[32:35], v[136:139], v[206:209], 0
	v_mfma_f32_16x16x32_bf16 v[36:39], v[128:131], v[206:209], 0
	v_mfma_f32_16x16x32_bf16 v[20:23], v[128:131], v[214:217], 0
	v_mfma_f32_16x16x32_bf16 v[16:19], v[136:139], v[214:217], 0
	v_mfma_f32_16x16x32_bf16 v[0:3], v[136:139], v[222:225], 0
	v_mfma_f32_16x16x32_bf16 v[4:7], v[128:131], v[222:225], 0
	v_mfma_f32_16x16x32_bf16 v[52:55], v[132:135], v[202:205], v[52:55]
	v_mfma_f32_16x16x32_bf16 v[48:51], v[140:143], v[202:205], v[48:51]
	v_mfma_f32_16x16x32_bf16 v[32:35], v[140:143], v[210:213], v[32:35]
	v_mfma_f32_16x16x32_bf16 v[36:39], v[132:135], v[210:213], v[36:39]
	v_mfma_f32_16x16x32_bf16 v[20:23], v[132:135], v[218:221], v[20:23]
	v_mfma_f32_16x16x32_bf16 v[16:19], v[140:143], v[218:221], v[16:19]
	v_mfma_f32_16x16x32_bf16 v[0:3], v[140:143], v[226:229], v[0:3]
	v_mfma_f32_16x16x32_bf16 v[4:7], v[132:135], v[226:229], v[4:7]
	v_mfma_f32_16x16x32_bf16 v[60:63], v[144:147], v[178:181], 0
	v_mfma_f32_16x16x32_bf16 v[56:59], v[170:173], v[178:181], 0
	v_mfma_f32_16x16x32_bf16 v[40:43], v[170:173], v[206:209], 0
	v_mfma_f32_16x16x32_bf16 v[44:47], v[144:147], v[206:209], 0
	v_mfma_f32_16x16x32_bf16 v[28:31], v[144:147], v[214:217], 0
	v_mfma_f32_16x16x32_bf16 v[24:27], v[170:173], v[214:217], 0
	v_mfma_f32_16x16x32_bf16 v[8:11], v[170:173], v[222:225], 0
	v_mfma_f32_16x16x32_bf16 v[12:15], v[144:147], v[222:225], 0
	v_mfma_f32_16x16x32_bf16 v[60:63], v[148:151], v[202:205], v[60:63]
	v_mfma_f32_16x16x32_bf16 v[56:59], v[174:177], v[202:205], v[56:59]
	v_mfma_f32_16x16x32_bf16 v[40:43], v[174:177], v[210:213], v[40:43]
	v_mfma_f32_16x16x32_bf16 v[44:47], v[148:151], v[210:213], v[44:47]
	v_mfma_f32_16x16x32_bf16 v[28:31], v[148:151], v[218:221], v[28:31]
	v_mfma_f32_16x16x32_bf16 v[24:27], v[174:177], v[218:221], v[24:27]
	v_mfma_f32_16x16x32_bf16 v[8:11], v[174:177], v[226:229], v[8:11]
	v_mfma_f32_16x16x32_bf16 v[12:15], v[148:151], v[226:229], v[12:15]
	s_setprio 0
	s_barrier
	s_add_i32 s2, 0, 0x18000
	s_add_i32 s12, 0, 0x1c000
	v_add_u32_e32 v140, s2, v195
	v_add_u32_e32 v174, s12, v195
	ds_read_b128 v[128:131], v140
	ds_read_b128 v[132:135], v140 offset:1024
	ds_read_b128 v[136:139], v140 offset:2048
	ds_read_b128 v[140:143], v140 offset:3072
	ds_read_b128 v[144:147], v174
	ds_read_b128 v[148:151], v174 offset:1024
	ds_read_b128 v[170:173], v174 offset:2048
	ds_read_b128 v[174:177], v174 offset:3072
	s_add_u32 s0, s0, s8
	s_addc_u32 s1, s1, s9
	s_mov_b32 m0, s28
	v_lshl_add_u64 v[242:243], s[0:1], 0, v[158:159]
	ds_read_b128 v[178:181], v157 offset:32768
	ds_read_b128 v[202:205], v157 offset:33792
	ds_read_b128 v[206:209], v157 offset:34816
	ds_read_b128 v[210:213], v157 offset:35840
	ds_read_b128 v[214:217], v157 offset:36864
	ds_read_b128 v[218:221], v157 offset:37888
	ds_read_b128 v[222:225], v157 offset:38912
	ds_read_b128 v[226:229], v157 offset:39936
	global_load_lds_dwordx4 v[242:243], off
	v_lshl_add_u64 v[242:243], s[0:1], 0, v[160:161]
	s_mov_b32 m0, s29
	s_nop 0
	global_load_lds_dwordx4 v[242:243], off
	s_waitcnt vmcnt(10)
	s_waitcnt lgkmcnt(0)
	s_barrier
	s_setprio 1
	s_waitcnt lgkmcnt(0)
	v_mfma_f32_16x16x32_bf16 v[120:123], v[128:131], v[178:181], v[120:123]
	v_mfma_f32_16x16x32_bf16 v[124:127], v[136:139], v[178:181], v[124:127]
	v_mfma_f32_16x16x32_bf16 v[96:99], v[136:139], v[206:209], v[96:99]
	v_mfma_f32_16x16x32_bf16 v[100:103], v[128:131], v[206:209], v[100:103]
	v_mfma_f32_16x16x32_bf16 v[84:87], v[128:131], v[214:217], v[84:87]
	v_mfma_f32_16x16x32_bf16 v[80:83], v[136:139], v[214:217], v[80:83]
	v_mfma_f32_16x16x32_bf16 v[64:67], v[136:139], v[222:225], v[64:67]
	v_mfma_f32_16x16x32_bf16 v[68:71], v[128:131], v[222:225], v[68:71]
	v_mfma_f32_16x16x32_bf16 v[120:123], v[132:135], v[202:205], v[120:123]
	v_mfma_f32_16x16x32_bf16 v[124:127], v[140:143], v[202:205], v[124:127]
	v_mfma_f32_16x16x32_bf16 v[96:99], v[140:143], v[210:213], v[96:99]
	v_mfma_f32_16x16x32_bf16 v[100:103], v[132:135], v[210:213], v[100:103]
	v_mfma_f32_16x16x32_bf16 v[84:87], v[132:135], v[218:221], v[84:87]
	v_mfma_f32_16x16x32_bf16 v[80:83], v[140:143], v[218:221], v[80:83]
	v_mfma_f32_16x16x32_bf16 v[64:67], v[140:143], v[226:229], v[64:67]
	v_mfma_f32_16x16x32_bf16 v[68:71], v[132:135], v[226:229], v[68:71]
	v_mfma_f32_16x16x32_bf16 v[116:119], v[144:147], v[178:181], v[116:119]
	v_mfma_f32_16x16x32_bf16 v[112:115], v[170:173], v[178:181], v[112:115]
	v_mfma_f32_16x16x32_bf16 v[104:107], v[170:173], v[206:209], v[104:107]
	v_mfma_f32_16x16x32_bf16 v[108:111], v[144:147], v[206:209], v[108:111]
	v_mfma_f32_16x16x32_bf16 v[92:95], v[144:147], v[214:217], v[92:95]
	v_mfma_f32_16x16x32_bf16 v[88:91], v[170:173], v[214:217], v[88:91]
	v_mfma_f32_16x16x32_bf16 v[72:75], v[170:173], v[222:225], v[72:75]
	v_mfma_f32_16x16x32_bf16 v[76:79], v[144:147], v[222:225], v[76:79]
	v_mfma_f32_16x16x32_bf16 v[116:119], v[148:151], v[202:205], v[116:119]
	v_mfma_f32_16x16x32_bf16 v[112:115], v[174:177], v[202:205], v[112:115]
	v_mfma_f32_16x16x32_bf16 v[104:107], v[174:177], v[210:213], v[104:107]
	v_mfma_f32_16x16x32_bf16 v[108:111], v[148:151], v[210:213], v[108:111]
	v_mfma_f32_16x16x32_bf16 v[92:95], v[148:151], v[218:221], v[92:95]
	v_mfma_f32_16x16x32_bf16 v[88:91], v[174:177], v[218:221], v[88:91]
	v_mfma_f32_16x16x32_bf16 v[72:75], v[174:177], v[226:229], v[72:75]
	v_mfma_f32_16x16x32_bf16 v[76:79], v[148:151], v[226:229], v[76:79]
	s_setprio 0
	s_barrier
	s_add_i32 s0, s2, s17
	v_lshl_add_u64 v[230:231], v[230:231], 0, s[36:37]
	s_mov_b32 m0, s0
	ds_read_b128 v[178:181], v157 offset:49152
	ds_read_b128 v[202:205], v157 offset:50176
	ds_read_b128 v[206:209], v157 offset:51200
	ds_read_b128 v[210:213], v157 offset:52224
	ds_read_b128 v[214:217], v157 offset:53248
	ds_read_b128 v[218:221], v157 offset:54272
	ds_read_b128 v[222:225], v157 offset:55296
	ds_read_b128 v[226:229], v157 offset:56320
	global_load_lds_dwordx4 v[230:231], off
	v_lshl_add_u64 v[230:231], v[232:233], 0, s[36:37]
	s_add_i32 m0, s0, 0x2000
	s_add_i32 s0, s12, s17
	global_load_lds_dwordx4 v[230:231], off
	v_lshl_add_u64 v[230:231], v[234:235], 0, s[36:37]
	s_mov_b32 m0, s0
	s_nop 0
	global_load_lds_dwordx4 v[230:231], off
	v_lshl_add_u64 v[230:231], v[236:237], 0, s[36:37]
	s_add_i32 m0, s0, 0x2000
	s_nop 0
	global_load_lds_dwordx4 v[230:231], off
	v_lshl_add_u64 v[230:231], v[238:239], 0, s[36:37]
	s_mov_b32 m0, s10
	s_nop 0
	global_load_lds_dwordx4 v[230:231], off
	v_lshl_add_u64 v[230:231], v[240:241], 0, s[36:37]
	s_mov_b32 m0, s11
	s_nop 0
	global_load_lds_dwordx4 v[230:231], off
	s_waitcnt vmcnt(10)
	s_waitcnt lgkmcnt(0)
	s_barrier
	s_setprio 1
	s_waitcnt lgkmcnt(0)
	v_mfma_f32_16x16x32_bf16 v[52:55], v[128:131], v[178:181], v[52:55]
	v_mfma_f32_16x16x32_bf16 v[48:51], v[136:139], v[178:181], v[48:51]
	v_mfma_f32_16x16x32_bf16 v[32:35], v[136:139], v[206:209], v[32:35]
	v_mfma_f32_16x16x32_bf16 v[36:39], v[128:131], v[206:209], v[36:39]
	v_mfma_f32_16x16x32_bf16 v[20:23], v[128:131], v[214:217], v[20:23]
	v_mfma_f32_16x16x32_bf16 v[16:19], v[136:139], v[214:217], v[16:19]
	v_mfma_f32_16x16x32_bf16 v[0:3], v[136:139], v[222:225], v[0:3]
	v_mfma_f32_16x16x32_bf16 v[4:7], v[128:131], v[222:225], v[4:7]
	v_mfma_f32_16x16x32_bf16 v[52:55], v[132:135], v[202:205], v[52:55]
	v_mfma_f32_16x16x32_bf16 v[48:51], v[140:143], v[202:205], v[48:51]
	v_mfma_f32_16x16x32_bf16 v[32:35], v[140:143], v[210:213], v[32:35]
	v_mfma_f32_16x16x32_bf16 v[36:39], v[132:135], v[210:213], v[36:39]
	v_mfma_f32_16x16x32_bf16 v[20:23], v[132:135], v[218:221], v[20:23]
	v_mfma_f32_16x16x32_bf16 v[16:19], v[140:143], v[218:221], v[16:19]
	v_mfma_f32_16x16x32_bf16 v[0:3], v[140:143], v[226:229], v[0:3]
	v_mfma_f32_16x16x32_bf16 v[4:7], v[132:135], v[226:229], v[4:7]
	v_mfma_f32_16x16x32_bf16 v[60:63], v[144:147], v[178:181], v[60:63]
	v_mfma_f32_16x16x32_bf16 v[56:59], v[170:173], v[178:181], v[56:59]
	v_mfma_f32_16x16x32_bf16 v[40:43], v[170:173], v[206:209], v[40:43]
	v_mfma_f32_16x16x32_bf16 v[44:47], v[144:147], v[206:209], v[44:47]
	v_mfma_f32_16x16x32_bf16 v[28:31], v[144:147], v[214:217], v[28:31]
	v_mfma_f32_16x16x32_bf16 v[24:27], v[170:173], v[214:217], v[24:27]
	v_mfma_f32_16x16x32_bf16 v[8:11], v[170:173], v[222:225], v[8:11]
	v_mfma_f32_16x16x32_bf16 v[12:15], v[144:147], v[222:225], v[12:15]
	v_mfma_f32_16x16x32_bf16 v[60:63], v[148:151], v[202:205], v[60:63]
	v_mfma_f32_16x16x32_bf16 v[56:59], v[174:177], v[202:205], v[56:59]
	v_mfma_f32_16x16x32_bf16 v[40:43], v[174:177], v[210:213], v[40:43]
	v_mfma_f32_16x16x32_bf16 v[44:47], v[148:151], v[210:213], v[44:47]
	v_mfma_f32_16x16x32_bf16 v[28:31], v[148:151], v[218:221], v[28:31]
	v_mfma_f32_16x16x32_bf16 v[24:27], v[174:177], v[218:221], v[24:27]
	v_mfma_f32_16x16x32_bf16 v[8:11], v[174:177], v[226:229], v[8:11]
	v_mfma_f32_16x16x32_bf16 v[12:15], v[148:151], v[226:229], v[12:15]
	s_setprio 0
	s_barrier
	s_add_u32 s42, s42, 0x100
	s_addc_u32 s43, s43, 0
	s_add_u32 s46, s46, 0x100
	s_addc_u32 s47, s47, 0
	s_cmp_ge_u32 s97, s31
	s_mov_b32 s0, s97
.LBB0_375:
	s_add_i32 s97, s0, 2
	s_add_u32 s2, s42, 0x80
	s_addc_u32 s1, s43, 0
	s_add_i32 s12, 0, 0x10000
	s_cmp_eq_u32 s13, s0
	s_cselect_b32 s1, s95, s1
	s_cselect_b32 s0, s94, s2
	s_cselect_b32 s15, s55, s47
	s_cselect_b32 s14, s54, s46
	s_add_i32 s2, 0, 0x14000
	v_add_u32_e32 v140, s12, v195
	v_add_u32_e32 v174, s2, v195
	ds_read_b128 v[128:131], v140
	ds_read_b128 v[132:135], v140 offset:1024
	ds_read_b128 v[136:139], v140 offset:2048
	ds_read_b128 v[140:143], v140 offset:3072
	ds_read_b128 v[144:147], v174
	ds_read_b128 v[148:151], v174 offset:1024
	ds_read_b128 v[170:173], v174 offset:2048
	ds_read_b128 v[174:177], v174 offset:3072
	v_lshl_add_u64 v[230:231], s[42:43], 0, v[166:167]
	s_add_i32 m0, s45, 0xc000
	ds_read_b128 v[178:181], v157
	ds_read_b128 v[202:205], v157 offset:1024
	ds_read_b128 v[206:209], v157 offset:2048
	ds_read_b128 v[210:213], v157 offset:3072
	ds_read_b128 v[214:217], v157 offset:4096
	ds_read_b128 v[218:221], v157 offset:5120
	ds_read_b128 v[222:225], v157 offset:6144
	ds_read_b128 v[226:229], v157 offset:7168
	global_load_lds_dwordx4 v[230:231], off
	v_lshl_add_u64 v[230:231], s[42:43], 0, v[168:169]
	s_add_i32 m0, s45, 0xe000
	s_nop 0
	global_load_lds_dwordx4 v[230:231], off
	s_waitcnt vmcnt(8)
	s_waitcnt lgkmcnt(0)
	s_barrier
	s_setprio 1
	s_waitcnt lgkmcnt(0)
	v_mfma_f32_16x16x32_bf16 v[120:123], v[128:131], v[178:181], v[120:123]
	v_mfma_f32_16x16x32_bf16 v[124:127], v[136:139], v[178:181], v[124:127]
	v_mfma_f32_16x16x32_bf16 v[96:99], v[136:139], v[206:209], v[96:99]
	v_mfma_f32_16x16x32_bf16 v[100:103], v[128:131], v[206:209], v[100:103]
	v_mfma_f32_16x16x32_bf16 v[84:87], v[128:131], v[214:217], v[84:87]
	v_mfma_f32_16x16x32_bf16 v[80:83], v[136:139], v[214:217], v[80:83]
	v_mfma_f32_16x16x32_bf16 v[64:67], v[136:139], v[222:225], v[64:67]
	v_mfma_f32_16x16x32_bf16 v[68:71], v[128:131], v[222:225], v[68:71]
	v_mfma_f32_16x16x32_bf16 v[120:123], v[132:135], v[202:205], v[120:123]
	v_mfma_f32_16x16x32_bf16 v[124:127], v[140:143], v[202:205], v[124:127]
	v_mfma_f32_16x16x32_bf16 v[96:99], v[140:143], v[210:213], v[96:99]
	v_mfma_f32_16x16x32_bf16 v[100:103], v[132:135], v[210:213], v[100:103]
	v_mfma_f32_16x16x32_bf16 v[84:87], v[132:135], v[218:221], v[84:87]
	v_mfma_f32_16x16x32_bf16 v[80:83], v[140:143], v[218:221], v[80:83]
	v_mfma_f32_16x16x32_bf16 v[64:67], v[140:143], v[226:229], v[64:67]
	v_mfma_f32_16x16x32_bf16 v[68:71], v[132:135], v[226:229], v[68:71]
	v_mfma_f32_16x16x32_bf16 v[116:119], v[144:147], v[178:181], v[116:119]
	v_mfma_f32_16x16x32_bf16 v[112:115], v[170:173], v[178:181], v[112:115]
	v_mfma_f32_16x16x32_bf16 v[104:107], v[170:173], v[206:209], v[104:107]
	v_mfma_f32_16x16x32_bf16 v[108:111], v[144:147], v[206:209], v[108:111]
	v_mfma_f32_16x16x32_bf16 v[92:95], v[144:147], v[214:217], v[92:95]
	v_mfma_f32_16x16x32_bf16 v[88:91], v[170:173], v[214:217], v[88:91]
	v_mfma_f32_16x16x32_bf16 v[72:75], v[170:173], v[222:225], v[72:75]
	v_mfma_f32_16x16x32_bf16 v[76:79], v[144:147], v[222:225], v[76:79]
	v_mfma_f32_16x16x32_bf16 v[116:119], v[148:151], v[202:205], v[116:119]
	v_mfma_f32_16x16x32_bf16 v[112:115], v[174:177], v[202:205], v[112:115]
	v_mfma_f32_16x16x32_bf16 v[104:107], v[174:177], v[210:213], v[104:107]
	v_mfma_f32_16x16x32_bf16 v[108:111], v[148:151], v[210:213], v[108:111]
	v_mfma_f32_16x16x32_bf16 v[92:95], v[148:151], v[218:221], v[92:95]
	v_mfma_f32_16x16x32_bf16 v[88:91], v[174:177], v[218:221], v[88:91]
	v_mfma_f32_16x16x32_bf16 v[72:75], v[174:177], v[226:229], v[72:75]
	v_mfma_f32_16x16x32_bf16 v[76:79], v[148:151], v[226:229], v[76:79]
	s_setprio 0
	s_barrier
	s_add_i32 s12, s12, s17
	v_lshl_add_u64 v[230:231], s[14:15], 0, v[154:155]
	s_mov_b32 m0, s12
	ds_read_b128 v[178:181], v157 offset:16384
	ds_read_b128 v[202:205], v157 offset:17408
	ds_read_b128 v[206:209], v157 offset:18432
	ds_read_b128 v[210:213], v157 offset:19456
	ds_read_b128 v[214:217], v157 offset:20480
	ds_read_b128 v[218:221], v157 offset:21504
	ds_read_b128 v[222:225], v157 offset:22528
	ds_read_b128 v[226:229], v157 offset:23552
	global_load_lds_dwordx4 v[230:231], off
	s_add_i32 m0, s12, 0x2000
	v_lshl_add_u64 v[232:233], s[14:15], 0, v[162:163]
	s_add_u32 s14, s14, s24
	s_addc_u32 s15, s15, s25
	s_add_i32 s2, s2, s17
	global_load_lds_dwordx4 v[232:233], off
	v_lshl_add_u64 v[234:235], s[14:15], 0, v[154:155]
	s_mov_b32 m0, s2
	v_lshl_add_u64 v[236:237], s[14:15], 0, v[162:163]
	global_load_lds_dwordx4 v[234:235], off
	s_add_i32 m0, s2, 0x2000
	v_lshl_add_u64 v[238:239], s[0:1], 0, v[158:159]
	global_load_lds_dwordx4 v[236:237], off
	s_mov_b32 m0, s45
	v_lshl_add_u64 v[240:241], s[0:1], 0, v[160:161]
	global_load_lds_dwordx4 v[238:239], off
	s_mov_b32 m0, s83
	s_nop 0
	global_load_lds_dwordx4 v[240:241], off
	s_waitcnt vmcnt(8)
	s_waitcnt lgkmcnt(0)
	s_barrier
	s_setprio 1
	s_waitcnt lgkmcnt(0)
	v_mfma_f32_16x16x32_bf16 v[52:55], v[128:131], v[178:181], v[52:55]
	v_mfma_f32_16x16x32_bf16 v[48:51], v[136:139], v[178:181], v[48:51]
	v_mfma_f32_16x16x32_bf16 v[32:35], v[136:139], v[206:209], v[32:35]
	v_mfma_f32_16x16x32_bf16 v[36:39], v[128:131], v[206:209], v[36:39]
	v_mfma_f32_16x16x32_bf16 v[20:23], v[128:131], v[214:217], v[20:23]
	v_mfma_f32_16x16x32_bf16 v[16:19], v[136:139], v[214:217], v[16:19]
	v_mfma_f32_16x16x32_bf16 v[0:3], v[136:139], v[222:225], v[0:3]
	v_mfma_f32_16x16x32_bf16 v[4:7], v[128:131], v[222:225], v[4:7]
	v_mfma_f32_16x16x32_bf16 v[52:55], v[132:135], v[202:205], v[52:55]
	v_mfma_f32_16x16x32_bf16 v[48:51], v[140:143], v[202:205], v[48:51]
	v_mfma_f32_16x16x32_bf16 v[32:35], v[140:143], v[210:213], v[32:35]
	v_mfma_f32_16x16x32_bf16 v[36:39], v[132:135], v[210:213], v[36:39]
	v_mfma_f32_16x16x32_bf16 v[20:23], v[132:135], v[218:221], v[20:23]
	v_mfma_f32_16x16x32_bf16 v[16:19], v[140:143], v[218:221], v[16:19]
	v_mfma_f32_16x16x32_bf16 v[0:3], v[140:143], v[226:229], v[0:3]
	v_mfma_f32_16x16x32_bf16 v[4:7], v[132:135], v[226:229], v[4:7]
	v_mfma_f32_16x16x32_bf16 v[60:63], v[144:147], v[178:181], v[60:63]
	v_mfma_f32_16x16x32_bf16 v[56:59], v[170:173], v[178:181], v[56:59]
	v_mfma_f32_16x16x32_bf16 v[40:43], v[170:173], v[206:209], v[40:43]
	v_mfma_f32_16x16x32_bf16 v[44:47], v[144:147], v[206:209], v[44:47]
	v_mfma_f32_16x16x32_bf16 v[28:31], v[144:147], v[214:217], v[28:31]
	v_mfma_f32_16x16x32_bf16 v[24:27], v[170:173], v[214:217], v[24:27]
	v_mfma_f32_16x16x32_bf16 v[8:11], v[170:173], v[222:225], v[8:11]
	v_mfma_f32_16x16x32_bf16 v[12:15], v[144:147], v[222:225], v[12:15]
	v_mfma_f32_16x16x32_bf16 v[60:63], v[148:151], v[202:205], v[60:63]
	v_mfma_f32_16x16x32_bf16 v[56:59], v[174:177], v[202:205], v[56:59]
	v_mfma_f32_16x16x32_bf16 v[40:43], v[174:177], v[210:213], v[40:43]
	v_mfma_f32_16x16x32_bf16 v[44:47], v[148:151], v[210:213], v[44:47]
	v_mfma_f32_16x16x32_bf16 v[28:31], v[148:151], v[218:221], v[28:31]
	v_mfma_f32_16x16x32_bf16 v[24:27], v[174:177], v[218:221], v[24:27]
	v_mfma_f32_16x16x32_bf16 v[8:11], v[174:177], v[226:229], v[8:11]
	v_mfma_f32_16x16x32_bf16 v[12:15], v[148:151], v[226:229], v[12:15]
	s_setprio 0
	s_barrier
	s_add_i32 s2, 0, 0x18000
	s_add_i32 s12, 0, 0x1c000
	v_add_u32_e32 v140, s2, v195
	v_add_u32_e32 v174, s12, v195
	ds_read_b128 v[128:131], v140
	ds_read_b128 v[132:135], v140 offset:1024
	ds_read_b128 v[136:139], v140 offset:2048
	ds_read_b128 v[140:143], v140 offset:3072
	ds_read_b128 v[144:147], v174
	ds_read_b128 v[148:151], v174 offset:1024
	ds_read_b128 v[170:173], v174 offset:2048
	ds_read_b128 v[174:177], v174 offset:3072
	s_add_u32 s0, s0, s8
	s_addc_u32 s1, s1, s9
	s_mov_b32 m0, s28
	v_lshl_add_u64 v[242:243], s[0:1], 0, v[158:159]
	ds_read_b128 v[178:181], v157 offset:32768
	ds_read_b128 v[202:205], v157 offset:33792
	ds_read_b128 v[206:209], v157 offset:34816
	ds_read_b128 v[210:213], v157 offset:35840
	ds_read_b128 v[214:217], v157 offset:36864
	ds_read_b128 v[218:221], v157 offset:37888
	ds_read_b128 v[222:225], v157 offset:38912
	ds_read_b128 v[226:229], v157 offset:39936
	global_load_lds_dwordx4 v[242:243], off
	v_lshl_add_u64 v[242:243], s[0:1], 0, v[160:161]
	s_mov_b32 m0, s29
	s_nop 0
	global_load_lds_dwordx4 v[242:243], off
	s_waitcnt vmcnt(8)
	s_waitcnt lgkmcnt(0)
	s_barrier
	s_setprio 1
	s_waitcnt lgkmcnt(0)
	v_mfma_f32_16x16x32_bf16 v[120:123], v[128:131], v[178:181], v[120:123]
	v_mfma_f32_16x16x32_bf16 v[124:127], v[136:139], v[178:181], v[124:127]
	v_mfma_f32_16x16x32_bf16 v[96:99], v[136:139], v[206:209], v[96:99]
	v_mfma_f32_16x16x32_bf16 v[100:103], v[128:131], v[206:209], v[100:103]
	v_mfma_f32_16x16x32_bf16 v[84:87], v[128:131], v[214:217], v[84:87]
	v_mfma_f32_16x16x32_bf16 v[80:83], v[136:139], v[214:217], v[80:83]
	v_mfma_f32_16x16x32_bf16 v[64:67], v[136:139], v[222:225], v[64:67]
	v_mfma_f32_16x16x32_bf16 v[68:71], v[128:131], v[222:225], v[68:71]
	v_mfma_f32_16x16x32_bf16 v[120:123], v[132:135], v[202:205], v[120:123]
	v_mfma_f32_16x16x32_bf16 v[124:127], v[140:143], v[202:205], v[124:127]
	v_mfma_f32_16x16x32_bf16 v[96:99], v[140:143], v[210:213], v[96:99]
	v_mfma_f32_16x16x32_bf16 v[100:103], v[132:135], v[210:213], v[100:103]
	v_mfma_f32_16x16x32_bf16 v[84:87], v[132:135], v[218:221], v[84:87]
	v_mfma_f32_16x16x32_bf16 v[80:83], v[140:143], v[218:221], v[80:83]
	v_mfma_f32_16x16x32_bf16 v[64:67], v[140:143], v[226:229], v[64:67]
	v_mfma_f32_16x16x32_bf16 v[68:71], v[132:135], v[226:229], v[68:71]
	v_mfma_f32_16x16x32_bf16 v[116:119], v[144:147], v[178:181], v[116:119]
	v_mfma_f32_16x16x32_bf16 v[112:115], v[170:173], v[178:181], v[112:115]
	v_mfma_f32_16x16x32_bf16 v[104:107], v[170:173], v[206:209], v[104:107]
	v_mfma_f32_16x16x32_bf16 v[108:111], v[144:147], v[206:209], v[108:111]
	v_mfma_f32_16x16x32_bf16 v[92:95], v[144:147], v[214:217], v[92:95]
	v_mfma_f32_16x16x32_bf16 v[88:91], v[170:173], v[214:217], v[88:91]
	v_mfma_f32_16x16x32_bf16 v[72:75], v[170:173], v[222:225], v[72:75]
	v_mfma_f32_16x16x32_bf16 v[76:79], v[144:147], v[222:225], v[76:79]
	v_mfma_f32_16x16x32_bf16 v[116:119], v[148:151], v[202:205], v[116:119]
	v_mfma_f32_16x16x32_bf16 v[112:115], v[174:177], v[202:205], v[112:115]
	v_mfma_f32_16x16x32_bf16 v[104:107], v[174:177], v[210:213], v[104:107]
	v_mfma_f32_16x16x32_bf16 v[108:111], v[148:151], v[210:213], v[108:111]
	v_mfma_f32_16x16x32_bf16 v[92:95], v[148:151], v[218:221], v[92:95]
	v_mfma_f32_16x16x32_bf16 v[88:91], v[174:177], v[218:221], v[88:91]
	v_mfma_f32_16x16x32_bf16 v[72:75], v[174:177], v[226:229], v[72:75]
	v_mfma_f32_16x16x32_bf16 v[76:79], v[148:151], v[226:229], v[76:79]
	s_setprio 0
	s_barrier
	s_add_i32 s0, s2, s17
	v_lshl_add_u64 v[230:231], v[230:231], 0, s[36:37]
	s_mov_b32 m0, s0
	ds_read_b128 v[178:181], v157 offset:49152
	ds_read_b128 v[202:205], v157 offset:50176
	ds_read_b128 v[206:209], v157 offset:51200
	ds_read_b128 v[210:213], v157 offset:52224
	ds_read_b128 v[214:217], v157 offset:53248
	ds_read_b128 v[218:221], v157 offset:54272
	ds_read_b128 v[222:225], v157 offset:55296
	ds_read_b128 v[226:229], v157 offset:56320
	global_load_lds_dwordx4 v[230:231], off
	v_lshl_add_u64 v[230:231], v[232:233], 0, s[36:37]
	s_add_i32 m0, s0, 0x2000
	s_add_i32 s0, s12, s17
	global_load_lds_dwordx4 v[230:231], off
	v_lshl_add_u64 v[230:231], v[234:235], 0, s[36:37]
	s_mov_b32 m0, s0
	s_nop 0
	global_load_lds_dwordx4 v[230:231], off
	v_lshl_add_u64 v[230:231], v[236:237], 0, s[36:37]
	s_add_i32 m0, s0, 0x2000
	s_nop 0
	global_load_lds_dwordx4 v[230:231], off
	v_lshl_add_u64 v[230:231], v[238:239], 0, s[36:37]
	s_mov_b32 m0, s10
	s_nop 0
	global_load_lds_dwordx4 v[230:231], off
	v_lshl_add_u64 v[230:231], v[240:241], 0, s[36:37]
	s_mov_b32 m0, s11
	s_nop 0
	global_load_lds_dwordx4 v[230:231], off
	s_waitcnt vmcnt(8)
	s_waitcnt lgkmcnt(0)
	s_barrier
	s_setprio 1
	s_waitcnt lgkmcnt(0)
	v_mfma_f32_16x16x32_bf16 v[52:55], v[128:131], v[178:181], v[52:55]
	v_mfma_f32_16x16x32_bf16 v[48:51], v[136:139], v[178:181], v[48:51]
	v_mfma_f32_16x16x32_bf16 v[32:35], v[136:139], v[206:209], v[32:35]
	v_mfma_f32_16x16x32_bf16 v[36:39], v[128:131], v[206:209], v[36:39]
	v_mfma_f32_16x16x32_bf16 v[20:23], v[128:131], v[214:217], v[20:23]
	v_mfma_f32_16x16x32_bf16 v[16:19], v[136:139], v[214:217], v[16:19]
	v_mfma_f32_16x16x32_bf16 v[0:3], v[136:139], v[222:225], v[0:3]
	v_mfma_f32_16x16x32_bf16 v[4:7], v[128:131], v[222:225], v[4:7]
	v_mfma_f32_16x16x32_bf16 v[52:55], v[132:135], v[202:205], v[52:55]
	v_mfma_f32_16x16x32_bf16 v[48:51], v[140:143], v[202:205], v[48:51]
	v_mfma_f32_16x16x32_bf16 v[32:35], v[140:143], v[210:213], v[32:35]
	v_mfma_f32_16x16x32_bf16 v[36:39], v[132:135], v[210:213], v[36:39]
	v_mfma_f32_16x16x32_bf16 v[20:23], v[132:135], v[218:221], v[20:23]
	v_mfma_f32_16x16x32_bf16 v[16:19], v[140:143], v[218:221], v[16:19]
	v_mfma_f32_16x16x32_bf16 v[0:3], v[140:143], v[226:229], v[0:3]
	v_mfma_f32_16x16x32_bf16 v[4:7], v[132:135], v[226:229], v[4:7]
	v_mfma_f32_16x16x32_bf16 v[60:63], v[144:147], v[178:181], v[60:63]
	v_mfma_f32_16x16x32_bf16 v[56:59], v[170:173], v[178:181], v[56:59]
	v_mfma_f32_16x16x32_bf16 v[40:43], v[170:173], v[206:209], v[40:43]
	v_mfma_f32_16x16x32_bf16 v[44:47], v[144:147], v[206:209], v[44:47]
	v_mfma_f32_16x16x32_bf16 v[28:31], v[144:147], v[214:217], v[28:31]
	v_mfma_f32_16x16x32_bf16 v[24:27], v[170:173], v[214:217], v[24:27]
	v_mfma_f32_16x16x32_bf16 v[8:11], v[170:173], v[222:225], v[8:11]
	v_mfma_f32_16x16x32_bf16 v[12:15], v[144:147], v[222:225], v[12:15]
	v_mfma_f32_16x16x32_bf16 v[60:63], v[148:151], v[202:205], v[60:63]
	v_mfma_f32_16x16x32_bf16 v[56:59], v[174:177], v[202:205], v[56:59]
	v_mfma_f32_16x16x32_bf16 v[40:43], v[174:177], v[210:213], v[40:43]
	v_mfma_f32_16x16x32_bf16 v[44:47], v[148:151], v[210:213], v[44:47]
	v_mfma_f32_16x16x32_bf16 v[28:31], v[148:151], v[218:221], v[28:31]
	v_mfma_f32_16x16x32_bf16 v[24:27], v[174:177], v[218:221], v[24:27]
	v_mfma_f32_16x16x32_bf16 v[8:11], v[174:177], v[226:229], v[8:11]
	v_mfma_f32_16x16x32_bf16 v[12:15], v[148:151], v[226:229], v[12:15]
	s_setprio 0
	s_barrier
	s_add_u32 s42, s42, 0x100
	s_addc_u32 s43, s43, 0
	s_add_u32 s46, s46, 0x100
	s_addc_u32 s47, s47, 0
	s_cmp_ge_u32 s97, s31
	s_mov_b32 s0, s97
	s_cbranch_scc0 .LBB0_375
	s_and_b64 vcc, exec, s[74:75]
	s_cbranch_vccz .LBB0_378
	s_barrier

.Lpeel_join482_1:
	s_waitcnt lgkmcnt(0)
	s_barrier
	s_setprio 1
	s_waitcnt lgkmcnt(0)
	v_mfma_f32_16x16x32_bf16 v[124:127], v[128:131], v[202:205], 0
	v_mfma_f32_16x16x32_bf16 v[120:123], v[146:149], v[202:205], 0
	v_mfma_f32_16x16x32_bf16 v[104:107], v[146:149], v[210:213], 0
	v_mfma_f32_16x16x32_bf16 v[108:111], v[128:131], v[210:213], 0
	v_mfma_f32_16x16x32_bf16 v[92:95], v[128:131], v[218:221], 0
	v_mfma_f32_16x16x32_bf16 v[88:91], v[146:149], v[218:221], 0
	v_mfma_f32_16x16x32_bf16 v[72:75], v[146:149], v[226:229], 0
	v_mfma_f32_16x16x32_bf16 v[76:79], v[128:131], v[226:229], 0
	v_mfma_f32_16x16x32_bf16 v[124:127], v[132:135], v[206:209], v[124:127]
	v_mfma_f32_16x16x32_bf16 v[120:123], v[158:161], v[206:209], v[120:123]
	v_mfma_f32_16x16x32_bf16 v[104:107], v[158:161], v[214:217], v[104:107]
	v_mfma_f32_16x16x32_bf16 v[108:111], v[132:135], v[214:217], v[108:111]
	v_mfma_f32_16x16x32_bf16 v[92:95], v[132:135], v[222:225], v[92:95]
	v_mfma_f32_16x16x32_bf16 v[88:91], v[158:161], v[222:225], v[88:91]
	v_mfma_f32_16x16x32_bf16 v[72:75], v[158:161], v[230:233], v[72:75]
	v_mfma_f32_16x16x32_bf16 v[76:79], v[132:135], v[230:233], v[76:79]
	v_mfma_f32_16x16x32_bf16 v[116:119], v[168:171], v[202:205], 0
	v_mfma_f32_16x16x32_bf16 v[112:115], v[176:179], v[202:205], 0
	v_mfma_f32_16x16x32_bf16 v[96:99], v[176:179], v[210:213], 0
	v_mfma_f32_16x16x32_bf16 v[100:103], v[168:171], v[210:213], 0
	v_mfma_f32_16x16x32_bf16 v[84:87], v[168:171], v[218:221], 0
	v_mfma_f32_16x16x32_bf16 v[80:83], v[176:179], v[218:221], 0
	v_mfma_f32_16x16x32_bf16 v[64:67], v[176:179], v[226:229], 0
	v_mfma_f32_16x16x32_bf16 v[68:71], v[168:171], v[226:229], 0
	v_mfma_f32_16x16x32_bf16 v[116:119], v[172:175], v[206:209], v[116:119]
	v_mfma_f32_16x16x32_bf16 v[112:115], v[194:197], v[206:209], v[112:115]
	v_mfma_f32_16x16x32_bf16 v[96:99], v[194:197], v[214:217], v[96:99]
	v_mfma_f32_16x16x32_bf16 v[100:103], v[172:175], v[214:217], v[100:103]
	v_mfma_f32_16x16x32_bf16 v[84:87], v[172:175], v[222:225], v[84:87]
	v_mfma_f32_16x16x32_bf16 v[80:83], v[194:197], v[222:225], v[80:83]
	v_mfma_f32_16x16x32_bf16 v[64:67], v[194:197], v[230:233], v[64:67]
	v_mfma_f32_16x16x32_bf16 v[68:71], v[172:175], v[230:233], v[68:71]
	s_setprio 0
	s_barrier
	s_add_i32 s15, s15, s2
	v_lshl_add_u64 v[150:151], s[82:83], 0, v[154:155]
	s_mov_b32 m0, s15
	ds_read_b128 v[202:205], v167 offset:16384
	ds_read_b128 v[206:209], v167 offset:17408
	ds_read_b128 v[210:213], v167 offset:18432
	ds_read_b128 v[214:217], v167 offset:19456
	ds_read_b128 v[218:221], v167 offset:20480
	ds_read_b128 v[222:225], v167 offset:21504
	ds_read_b128 v[226:229], v167 offset:22528
	ds_read_b128 v[230:233], v167 offset:23552
	global_load_lds_dwordx4 v[150:151], off
	s_add_i32 m0, s15, 0x2000
	v_lshl_add_u64 v[162:163], s[82:83], 0, v[140:141]
	s_add_u32 s82, s82, s24
	s_addc_u32 s83, s83, s25
	s_add_i32 s14, s14, s2
	global_load_lds_dwordx4 v[162:163], off
	v_lshl_add_u64 v[180:181], s[82:83], 0, v[154:155]
	s_mov_b32 m0, s14
	v_lshl_add_u64 v[234:235], s[82:83], 0, v[140:141]
	global_load_lds_dwordx4 v[180:181], off
	s_add_i32 m0, s14, 0x2000
	v_lshl_add_u64 v[236:237], s[0:1], 0, v[136:137]
	global_load_lds_dwordx4 v[234:235], off
	s_mov_b32 m0, s3
	v_lshl_add_u64 v[238:239], s[0:1], 0, v[138:139]
	global_load_lds_dwordx4 v[236:237], off
	s_mov_b32 m0, s10
	s_nop 0
	global_load_lds_dwordx4 v[238:239], off
	s_cmp_eq_u32 s92, 1
	s_cbranch_scc1 .Lpeel_strict482_2
	s_waitcnt vmcnt(24)
	s_branch .Lpeel_join482_2

.Lpeel_join482_2:
	s_waitcnt lgkmcnt(0)
	s_barrier
	s_setprio 1
	s_waitcnt lgkmcnt(0)
	v_mfma_f32_16x16x32_bf16 v[60:63], v[128:131], v[202:205], 0
	v_mfma_f32_16x16x32_bf16 v[56:59], v[146:149], v[202:205], 0
	v_mfma_f32_16x16x32_bf16 v[40:43], v[146:149], v[210:213], 0
	v_mfma_f32_16x16x32_bf16 v[44:47], v[128:131], v[210:213], 0
	v_mfma_f32_16x16x32_bf16 v[28:31], v[128:131], v[218:221], 0
	v_mfma_f32_16x16x32_bf16 v[24:27], v[146:149], v[218:221], 0
	v_mfma_f32_16x16x32_bf16 v[8:11], v[146:149], v[226:229], 0
	v_mfma_f32_16x16x32_bf16 v[12:15], v[128:131], v[226:229], 0
	v_mfma_f32_16x16x32_bf16 v[60:63], v[132:135], v[206:209], v[60:63]
	v_mfma_f32_16x16x32_bf16 v[56:59], v[158:161], v[206:209], v[56:59]
	v_mfma_f32_16x16x32_bf16 v[40:43], v[158:161], v[214:217], v[40:43]
	v_mfma_f32_16x16x32_bf16 v[44:47], v[132:135], v[214:217], v[44:47]
	v_mfma_f32_16x16x32_bf16 v[28:31], v[132:135], v[222:225], v[28:31]
	v_mfma_f32_16x16x32_bf16 v[24:27], v[158:161], v[222:225], v[24:27]
	v_mfma_f32_16x16x32_bf16 v[8:11], v[158:161], v[230:233], v[8:11]
	v_mfma_f32_16x16x32_bf16 v[12:15], v[132:135], v[230:233], v[12:15]
	v_mfma_f32_16x16x32_bf16 v[52:55], v[168:171], v[202:205], 0
	v_mfma_f32_16x16x32_bf16 v[48:51], v[176:179], v[202:205], 0
	v_mfma_f32_16x16x32_bf16 v[32:35], v[176:179], v[210:213], 0
	v_mfma_f32_16x16x32_bf16 v[36:39], v[168:171], v[210:213], 0
	v_mfma_f32_16x16x32_bf16 v[20:23], v[168:171], v[218:221], 0
	v_mfma_f32_16x16x32_bf16 v[16:19], v[176:179], v[218:221], 0
	v_mfma_f32_16x16x32_bf16 v[0:3], v[176:179], v[226:229], 0
	v_mfma_f32_16x16x32_bf16 v[4:7], v[168:171], v[226:229], 0
	v_mfma_f32_16x16x32_bf16 v[52:55], v[172:175], v[206:209], v[52:55]
	v_mfma_f32_16x16x32_bf16 v[48:51], v[194:197], v[206:209], v[48:51]
	v_mfma_f32_16x16x32_bf16 v[32:35], v[194:197], v[214:217], v[32:35]
	v_mfma_f32_16x16x32_bf16 v[36:39], v[172:175], v[214:217], v[36:39]
	v_mfma_f32_16x16x32_bf16 v[20:23], v[172:175], v[222:225], v[20:23]
	v_mfma_f32_16x16x32_bf16 v[16:19], v[194:197], v[222:225], v[16:19]
	v_mfma_f32_16x16x32_bf16 v[0:3], v[194:197], v[230:233], v[0:3]
	v_mfma_f32_16x16x32_bf16 v[4:7], v[172:175], v[230:233], v[4:7]
	s_setprio 0
	s_barrier
	s_add_i32 s14, 0, 0x18000
	s_add_i32 s15, 0, 0x1c000
	v_add_u32_e32 v158, s14, v165
	v_add_u32_e32 v193, s15, v165
	ds_read_b128 v[128:131], v158
	ds_read_b128 v[132:135], v158 offset:1024
	ds_read_b128 v[146:149], v158 offset:2048
	ds_read_b128 v[158:161], v158 offset:3072
	ds_read_b128 v[168:171], v193
	ds_read_b128 v[172:175], v193 offset:1024
	ds_read_b128 v[176:179], v193 offset:2048
	ds_read_b128 v[194:197], v193 offset:3072
	s_add_u32 s0, s0, s8
	s_addc_u32 s1, s1, s9
	s_mov_b32 m0, s11
	v_lshl_add_u64 v[240:241], s[0:1], 0, v[136:137]
	ds_read_b128 v[202:205], v167 offset:32768
	ds_read_b128 v[206:209], v167 offset:33792
	ds_read_b128 v[210:213], v167 offset:34816
	ds_read_b128 v[214:217], v167 offset:35840
	ds_read_b128 v[218:221], v167 offset:36864
	ds_read_b128 v[222:225], v167 offset:37888
	ds_read_b128 v[226:229], v167 offset:38912
	ds_read_b128 v[230:233], v167 offset:39936
	global_load_lds_dwordx4 v[240:241], off
	v_lshl_add_u64 v[240:241], s[0:1], 0, v[138:139]
	s_mov_b32 m0, s13
	s_nop 0
	global_load_lds_dwordx4 v[240:241], off
	s_waitcnt vmcnt(8)
	s_waitcnt lgkmcnt(0)
	s_barrier
	s_setprio 1
	s_waitcnt lgkmcnt(0)
	v_mfma_f32_16x16x32_bf16 v[124:127], v[128:131], v[202:205], v[124:127]
	v_mfma_f32_16x16x32_bf16 v[120:123], v[146:149], v[202:205], v[120:123]
	v_mfma_f32_16x16x32_bf16 v[104:107], v[146:149], v[210:213], v[104:107]
	v_mfma_f32_16x16x32_bf16 v[108:111], v[128:131], v[210:213], v[108:111]
	v_mfma_f32_16x16x32_bf16 v[92:95], v[128:131], v[218:221], v[92:95]
	v_mfma_f32_16x16x32_bf16 v[88:91], v[146:149], v[218:221], v[88:91]
	v_mfma_f32_16x16x32_bf16 v[72:75], v[146:149], v[226:229], v[72:75]
	v_mfma_f32_16x16x32_bf16 v[76:79], v[128:131], v[226:229], v[76:79]
	v_mfma_f32_16x16x32_bf16 v[124:127], v[132:135], v[206:209], v[124:127]
	v_mfma_f32_16x16x32_bf16 v[120:123], v[158:161], v[206:209], v[120:123]
	v_mfma_f32_16x16x32_bf16 v[104:107], v[158:161], v[214:217], v[104:107]
	v_mfma_f32_16x16x32_bf16 v[108:111], v[132:135], v[214:217], v[108:111]
	v_mfma_f32_16x16x32_bf16 v[92:95], v[132:135], v[222:225], v[92:95]
	v_mfma_f32_16x16x32_bf16 v[88:91], v[158:161], v[222:225], v[88:91]
	v_mfma_f32_16x16x32_bf16 v[72:75], v[158:161], v[230:233], v[72:75]
	v_mfma_f32_16x16x32_bf16 v[76:79], v[132:135], v[230:233], v[76:79]
	v_mfma_f32_16x16x32_bf16 v[116:119], v[168:171], v[202:205], v[116:119]
	v_mfma_f32_16x16x32_bf16 v[112:115], v[176:179], v[202:205], v[112:115]
	v_mfma_f32_16x16x32_bf16 v[96:99], v[176:179], v[210:213], v[96:99]
	v_mfma_f32_16x16x32_bf16 v[100:103], v[168:171], v[210:213], v[100:103]
	v_mfma_f32_16x16x32_bf16 v[84:87], v[168:171], v[218:221], v[84:87]
	v_mfma_f32_16x16x32_bf16 v[80:83], v[176:179], v[218:221], v[80:83]
	v_mfma_f32_16x16x32_bf16 v[64:67], v[176:179], v[226:229], v[64:67]
	v_mfma_f32_16x16x32_bf16 v[68:71], v[168:171], v[226:229], v[68:71]
	v_mfma_f32_16x16x32_bf16 v[116:119], v[172:175], v[206:209], v[116:119]
	v_mfma_f32_16x16x32_bf16 v[112:115], v[194:197], v[206:209], v[112:115]
	v_mfma_f32_16x16x32_bf16 v[96:99], v[194:197], v[214:217], v[96:99]
	v_mfma_f32_16x16x32_bf16 v[100:103], v[172:175], v[214:217], v[100:103]
	v_mfma_f32_16x16x32_bf16 v[84:87], v[172:175], v[222:225], v[84:87]
	v_mfma_f32_16x16x32_bf16 v[80:83], v[194:197], v[222:225], v[80:83]
	v_mfma_f32_16x16x32_bf16 v[64:67], v[194:197], v[230:233], v[64:67]
	v_mfma_f32_16x16x32_bf16 v[68:71], v[172:175], v[230:233], v[68:71]
	s_setprio 0
	s_barrier
	s_add_i32 s0, s14, s2
	v_lshl_add_u64 v[150:151], v[150:151], 0, s[36:37]
	s_mov_b32 m0, s0
	ds_read_b128 v[202:205], v167 offset:49152
	ds_read_b128 v[206:209], v167 offset:50176
	ds_read_b128 v[210:213], v167 offset:51200
	ds_read_b128 v[214:217], v167 offset:52224
	ds_read_b128 v[218:221], v167 offset:53248
	ds_read_b128 v[222:225], v167 offset:54272
	ds_read_b128 v[226:229], v167 offset:55296
	ds_read_b128 v[230:233], v167 offset:56320
	global_load_lds_dwordx4 v[150:151], off
	v_lshl_add_u64 v[150:151], v[162:163], 0, s[36:37]
	s_add_i32 m0, s0, 0x2000
	s_add_i32 s0, s15, s2
	global_load_lds_dwordx4 v[150:151], off
	v_lshl_add_u64 v[150:151], v[180:181], 0, s[36:37]
	s_mov_b32 m0, s0
	s_nop 0
	global_load_lds_dwordx4 v[150:151], off
	v_lshl_add_u64 v[150:151], v[234:235], 0, s[36:37]
	s_add_i32 m0, s0, 0x2000
	s_nop 0
	global_load_lds_dwordx4 v[150:151], off
	v_lshl_add_u64 v[150:151], v[236:237], 0, s[36:37]
	s_mov_b32 m0, s18
	s_nop 0
	global_load_lds_dwordx4 v[150:151], off
	v_lshl_add_u64 v[150:151], v[238:239], 0, s[36:37]
	s_mov_b32 m0, s28
	s_nop 0
	global_load_lds_dwordx4 v[150:151], off
	s_waitcnt vmcnt(8)
	s_waitcnt lgkmcnt(0)
	s_barrier
	s_setprio 1
	s_waitcnt lgkmcnt(0)
	v_mfma_f32_16x16x32_bf16 v[60:63], v[128:131], v[202:205], v[60:63]
	v_mfma_f32_16x16x32_bf16 v[56:59], v[146:149], v[202:205], v[56:59]
	v_mfma_f32_16x16x32_bf16 v[40:43], v[146:149], v[210:213], v[40:43]
	v_mfma_f32_16x16x32_bf16 v[44:47], v[128:131], v[210:213], v[44:47]
	v_mfma_f32_16x16x32_bf16 v[28:31], v[128:131], v[218:221], v[28:31]
	v_mfma_f32_16x16x32_bf16 v[24:27], v[146:149], v[218:221], v[24:27]
	v_mfma_f32_16x16x32_bf16 v[8:11], v[146:149], v[226:229], v[8:11]
	v_mfma_f32_16x16x32_bf16 v[12:15], v[128:131], v[226:229], v[12:15]
	v_mfma_f32_16x16x32_bf16 v[60:63], v[132:135], v[206:209], v[60:63]
	v_mfma_f32_16x16x32_bf16 v[56:59], v[158:161], v[206:209], v[56:59]
	v_mfma_f32_16x16x32_bf16 v[40:43], v[158:161], v[214:217], v[40:43]
	v_mfma_f32_16x16x32_bf16 v[44:47], v[132:135], v[214:217], v[44:47]
	v_mfma_f32_16x16x32_bf16 v[28:31], v[132:135], v[222:225], v[28:31]
	v_mfma_f32_16x16x32_bf16 v[24:27], v[158:161], v[222:225], v[24:27]
	v_mfma_f32_16x16x32_bf16 v[8:11], v[158:161], v[230:233], v[8:11]
	v_mfma_f32_16x16x32_bf16 v[12:15], v[132:135], v[230:233], v[12:15]
	v_mfma_f32_16x16x32_bf16 v[52:55], v[168:171], v[202:205], v[52:55]
	v_mfma_f32_16x16x32_bf16 v[48:51], v[176:179], v[202:205], v[48:51]
	v_mfma_f32_16x16x32_bf16 v[32:35], v[176:179], v[210:213], v[32:35]
	v_mfma_f32_16x16x32_bf16 v[36:39], v[168:171], v[210:213], v[36:39]
	v_mfma_f32_16x16x32_bf16 v[20:23], v[168:171], v[218:221], v[20:23]
	v_mfma_f32_16x16x32_bf16 v[16:19], v[176:179], v[218:221], v[16:19]
	v_mfma_f32_16x16x32_bf16 v[0:3], v[176:179], v[226:229], v[0:3]
	v_mfma_f32_16x16x32_bf16 v[4:7], v[168:171], v[226:229], v[4:7]
	v_mfma_f32_16x16x32_bf16 v[52:55], v[172:175], v[206:209], v[52:55]
	v_mfma_f32_16x16x32_bf16 v[48:51], v[194:197], v[206:209], v[48:51]
	v_mfma_f32_16x16x32_bf16 v[32:35], v[194:197], v[214:217], v[32:35]
	v_mfma_f32_16x16x32_bf16 v[36:39], v[172:175], v[214:217], v[36:39]
	v_mfma_f32_16x16x32_bf16 v[20:23], v[172:175], v[222:225], v[20:23]
	v_mfma_f32_16x16x32_bf16 v[16:19], v[194:197], v[222:225], v[16:19]
	v_mfma_f32_16x16x32_bf16 v[0:3], v[194:197], v[230:233], v[0:3]
	v_mfma_f32_16x16x32_bf16 v[4:7], v[172:175], v[230:233], v[4:7]
	s_setprio 0
	s_barrier
	s_add_u32 s42, s42, 0x100
	s_addc_u32 s43, s43, 0
	s_add_u32 s44, s44, 0x100
	s_addc_u32 s45, s45, 0
	s_cmp_ge_u32 s47, s31
	s_mov_b32 s0, s47
.LBB0_482:
	s_add_i32 s47, s0, 2
	s_add_u32 s14, s42, 0x80
	s_addc_u32 s1, s43, 0
	s_add_i32 s15, 0, 0x10000
	s_cmp_eq_u32 s29, s0
	s_cselect_b32 s1, s77, s1
	s_cselect_b32 s0, s76, s14
	v_add_u32_e32 v150, s15, v165
	s_cselect_b32 s83, s79, s45
	s_cselect_b32 s82, s78, s44
	s_add_i32 s14, 0, 0x14000
	ds_read_b128 v[128:131], v150
	ds_read_b128 v[132:135], v150 offset:1024
	ds_read_b128 v[146:149], v150 offset:2048
	ds_read_b128 v[158:161], v150 offset:3072
	v_add_u32_e32 v150, s14, v165
	ds_read_b128 v[168:171], v150
	ds_read_b128 v[172:175], v150 offset:1024
	ds_read_b128 v[176:179], v150 offset:2048
	ds_read_b128 v[194:197], v150 offset:3072
	v_lshl_add_u64 v[150:151], s[42:43], 0, v[142:143]
	s_add_i32 m0, s3, 0xc000
	ds_read_b128 v[202:205], v167
	ds_read_b128 v[206:209], v167 offset:1024
	ds_read_b128 v[210:213], v167 offset:2048
	ds_read_b128 v[214:217], v167 offset:3072
	ds_read_b128 v[218:221], v167 offset:4096
	ds_read_b128 v[222:225], v167 offset:5120
	ds_read_b128 v[226:229], v167 offset:6144
	ds_read_b128 v[230:233], v167 offset:7168
	global_load_lds_dwordx4 v[150:151], off
	v_lshl_add_u64 v[150:151], s[42:43], 0, v[144:145]
	s_add_i32 m0, s3, 0xe000
	s_nop 0
	global_load_lds_dwordx4 v[150:151], off
	s_waitcnt vmcnt(8)
	s_waitcnt lgkmcnt(0)
	s_barrier
	s_setprio 1
	s_waitcnt lgkmcnt(0)
	v_mfma_f32_16x16x32_bf16 v[124:127], v[128:131], v[202:205], v[124:127]
	v_mfma_f32_16x16x32_bf16 v[120:123], v[146:149], v[202:205], v[120:123]
	v_mfma_f32_16x16x32_bf16 v[104:107], v[146:149], v[210:213], v[104:107]
	v_mfma_f32_16x16x32_bf16 v[108:111], v[128:131], v[210:213], v[108:111]
	v_mfma_f32_16x16x32_bf16 v[92:95], v[128:131], v[218:221], v[92:95]
	v_mfma_f32_16x16x32_bf16 v[88:91], v[146:149], v[218:221], v[88:91]
	v_mfma_f32_16x16x32_bf16 v[72:75], v[146:149], v[226:229], v[72:75]
	v_mfma_f32_16x16x32_bf16 v[76:79], v[128:131], v[226:229], v[76:79]
	v_mfma_f32_16x16x32_bf16 v[124:127], v[132:135], v[206:209], v[124:127]
	v_mfma_f32_16x16x32_bf16 v[120:123], v[158:161], v[206:209], v[120:123]
	v_mfma_f32_16x16x32_bf16 v[104:107], v[158:161], v[214:217], v[104:107]
	v_mfma_f32_16x16x32_bf16 v[108:111], v[132:135], v[214:217], v[108:111]
	v_mfma_f32_16x16x32_bf16 v[92:95], v[132:135], v[222:225], v[92:95]
	v_mfma_f32_16x16x32_bf16 v[88:91], v[158:161], v[222:225], v[88:91]
	v_mfma_f32_16x16x32_bf16 v[72:75], v[158:161], v[230:233], v[72:75]
	v_mfma_f32_16x16x32_bf16 v[76:79], v[132:135], v[230:233], v[76:79]
	v_mfma_f32_16x16x32_bf16 v[116:119], v[168:171], v[202:205], v[116:119]
	v_mfma_f32_16x16x32_bf16 v[112:115], v[176:179], v[202:205], v[112:115]
	v_mfma_f32_16x16x32_bf16 v[96:99], v[176:179], v[210:213], v[96:99]
	v_mfma_f32_16x16x32_bf16 v[100:103], v[168:171], v[210:213], v[100:103]
	v_mfma_f32_16x16x32_bf16 v[84:87], v[168:171], v[218:221], v[84:87]
	v_mfma_f32_16x16x32_bf16 v[80:83], v[176:179], v[218:221], v[80:83]
	v_mfma_f32_16x16x32_bf16 v[64:67], v[176:179], v[226:229], v[64:67]
	v_mfma_f32_16x16x32_bf16 v[68:71], v[168:171], v[226:229], v[68:71]
	v_mfma_f32_16x16x32_bf16 v[116:119], v[172:175], v[206:209], v[116:119]
	v_mfma_f32_16x16x32_bf16 v[112:115], v[194:197], v[206:209], v[112:115]
	v_mfma_f32_16x16x32_bf16 v[96:99], v[194:197], v[214:217], v[96:99]
	v_mfma_f32_16x16x32_bf16 v[100:103], v[172:175], v[214:217], v[100:103]
	v_mfma_f32_16x16x32_bf16 v[84:87], v[172:175], v[222:225], v[84:87]
	v_mfma_f32_16x16x32_bf16 v[80:83], v[194:197], v[222:225], v[80:83]
	v_mfma_f32_16x16x32_bf16 v[64:67], v[194:197], v[230:233], v[64:67]
	v_mfma_f32_16x16x32_bf16 v[68:71], v[172:175], v[230:233], v[68:71]
	s_setprio 0
	s_barrier
	s_add_i32 s15, s15, s2
	v_lshl_add_u64 v[150:151], s[82:83], 0, v[154:155]
	s_mov_b32 m0, s15
	ds_read_b128 v[202:205], v167 offset:16384
	ds_read_b128 v[206:209], v167 offset:17408
	ds_read_b128 v[210:213], v167 offset:18432
	ds_read_b128 v[214:217], v167 offset:19456
	ds_read_b128 v[218:221], v167 offset:20480
	ds_read_b128 v[222:225], v167 offset:21504
	ds_read_b128 v[226:229], v167 offset:22528
	ds_read_b128 v[230:233], v167 offset:23552
	global_load_lds_dwordx4 v[150:151], off
	s_add_i32 m0, s15, 0x2000
	v_lshl_add_u64 v[162:163], s[82:83], 0, v[140:141]
	s_add_u32 s82, s82, s24
	s_addc_u32 s83, s83, s25
	s_add_i32 s14, s14, s2
	global_load_lds_dwordx4 v[162:163], off
	v_lshl_add_u64 v[180:181], s[82:83], 0, v[154:155]
	s_mov_b32 m0, s14
	v_lshl_add_u64 v[234:235], s[82:83], 0, v[140:141]
	global_load_lds_dwordx4 v[180:181], off
	s_add_i32 m0, s14, 0x2000
	v_lshl_add_u64 v[236:237], s[0:1], 0, v[136:137]
	global_load_lds_dwordx4 v[234:235], off
	s_mov_b32 m0, s3
	v_lshl_add_u64 v[238:239], s[0:1], 0, v[138:139]
	global_load_lds_dwordx4 v[236:237], off
	s_mov_b32 m0, s10
	s_nop 0
	global_load_lds_dwordx4 v[238:239], off
	s_waitcnt vmcnt(8)
	s_waitcnt lgkmcnt(0)
	s_barrier
	s_setprio 1
	s_waitcnt lgkmcnt(0)
	v_mfma_f32_16x16x32_bf16 v[60:63], v[128:131], v[202:205], v[60:63]
	v_mfma_f32_16x16x32_bf16 v[56:59], v[146:149], v[202:205], v[56:59]
	v_mfma_f32_16x16x32_bf16 v[40:43], v[146:149], v[210:213], v[40:43]
	v_mfma_f32_16x16x32_bf16 v[44:47], v[128:131], v[210:213], v[44:47]
	v_mfma_f32_16x16x32_bf16 v[28:31], v[128:131], v[218:221], v[28:31]
	v_mfma_f32_16x16x32_bf16 v[24:27], v[146:149], v[218:221], v[24:27]
	v_mfma_f32_16x16x32_bf16 v[8:11], v[146:149], v[226:229], v[8:11]
	v_mfma_f32_16x16x32_bf16 v[12:15], v[128:131], v[226:229], v[12:15]
	v_mfma_f32_16x16x32_bf16 v[60:63], v[132:135], v[206:209], v[60:63]
	v_mfma_f32_16x16x32_bf16 v[56:59], v[158:161], v[206:209], v[56:59]
	v_mfma_f32_16x16x32_bf16 v[40:43], v[158:161], v[214:217], v[40:43]
	v_mfma_f32_16x16x32_bf16 v[44:47], v[132:135], v[214:217], v[44:47]
	v_mfma_f32_16x16x32_bf16 v[28:31], v[132:135], v[222:225], v[28:31]
	v_mfma_f32_16x16x32_bf16 v[24:27], v[158:161], v[222:225], v[24:27]
	v_mfma_f32_16x16x32_bf16 v[8:11], v[158:161], v[230:233], v[8:11]
	v_mfma_f32_16x16x32_bf16 v[12:15], v[132:135], v[230:233], v[12:15]
	v_mfma_f32_16x16x32_bf16 v[52:55], v[168:171], v[202:205], v[52:55]
	v_mfma_f32_16x16x32_bf16 v[48:51], v[176:179], v[202:205], v[48:51]
	v_mfma_f32_16x16x32_bf16 v[32:35], v[176:179], v[210:213], v[32:35]
	v_mfma_f32_16x16x32_bf16 v[36:39], v[168:171], v[210:213], v[36:39]
	v_mfma_f32_16x16x32_bf16 v[20:23], v[168:171], v[218:221], v[20:23]
	v_mfma_f32_16x16x32_bf16 v[16:19], v[176:179], v[218:221], v[16:19]
	v_mfma_f32_16x16x32_bf16 v[0:3], v[176:179], v[226:229], v[0:3]
	v_mfma_f32_16x16x32_bf16 v[4:7], v[168:171], v[226:229], v[4:7]
	v_mfma_f32_16x16x32_bf16 v[52:55], v[172:175], v[206:209], v[52:55]
	v_mfma_f32_16x16x32_bf16 v[48:51], v[194:197], v[206:209], v[48:51]
	v_mfma_f32_16x16x32_bf16 v[32:35], v[194:197], v[214:217], v[32:35]
	v_mfma_f32_16x16x32_bf16 v[36:39], v[172:175], v[214:217], v[36:39]
	v_mfma_f32_16x16x32_bf16 v[20:23], v[172:175], v[222:225], v[20:23]
	v_mfma_f32_16x16x32_bf16 v[16:19], v[194:197], v[222:225], v[16:19]
	v_mfma_f32_16x16x32_bf16 v[0:3], v[194:197], v[230:233], v[0:3]
	v_mfma_f32_16x16x32_bf16 v[4:7], v[172:175], v[230:233], v[4:7]
	s_setprio 0
	s_barrier
	s_add_i32 s14, 0, 0x18000
	s_add_i32 s15, 0, 0x1c000
	v_add_u32_e32 v158, s14, v165
	v_add_u32_e32 v193, s15, v165
	ds_read_b128 v[128:131], v158
	ds_read_b128 v[132:135], v158 offset:1024
	ds_read_b128 v[146:149], v158 offset:2048
	ds_read_b128 v[158:161], v158 offset:3072
	ds_read_b128 v[168:171], v193
	ds_read_b128 v[172:175], v193 offset:1024
	ds_read_b128 v[176:179], v193 offset:2048
	ds_read_b128 v[194:197], v193 offset:3072
	s_add_u32 s0, s0, s8
	s_addc_u32 s1, s1, s9
	s_mov_b32 m0, s11
	v_lshl_add_u64 v[240:241], s[0:1], 0, v[136:137]
	ds_read_b128 v[202:205], v167 offset:32768
	ds_read_b128 v[206:209], v167 offset:33792
	ds_read_b128 v[210:213], v167 offset:34816
	ds_read_b128 v[214:217], v167 offset:35840
	ds_read_b128 v[218:221], v167 offset:36864
	ds_read_b128 v[222:225], v167 offset:37888
	ds_read_b128 v[226:229], v167 offset:38912
	ds_read_b128 v[230:233], v167 offset:39936
	global_load_lds_dwordx4 v[240:241], off
	v_lshl_add_u64 v[240:241], s[0:1], 0, v[138:139]
	s_mov_b32 m0, s13
	s_nop 0
	global_load_lds_dwordx4 v[240:241], off
	s_waitcnt vmcnt(8)
	s_waitcnt lgkmcnt(0)
	s_barrier
	s_setprio 1
	s_waitcnt lgkmcnt(0)
	v_mfma_f32_16x16x32_bf16 v[124:127], v[128:131], v[202:205], v[124:127]
	v_mfma_f32_16x16x32_bf16 v[120:123], v[146:149], v[202:205], v[120:123]
	v_mfma_f32_16x16x32_bf16 v[104:107], v[146:149], v[210:213], v[104:107]
	v_mfma_f32_16x16x32_bf16 v[108:111], v[128:131], v[210:213], v[108:111]
	v_mfma_f32_16x16x32_bf16 v[92:95], v[128:131], v[218:221], v[92:95]
	v_mfma_f32_16x16x32_bf16 v[88:91], v[146:149], v[218:221], v[88:91]
	v_mfma_f32_16x16x32_bf16 v[72:75], v[146:149], v[226:229], v[72:75]
	v_mfma_f32_16x16x32_bf16 v[76:79], v[128:131], v[226:229], v[76:79]
	v_mfma_f32_16x16x32_bf16 v[124:127], v[132:135], v[206:209], v[124:127]
	v_mfma_f32_16x16x32_bf16 v[120:123], v[158:161], v[206:209], v[120:123]
	v_mfma_f32_16x16x32_bf16 v[104:107], v[158:161], v[214:217], v[104:107]
	v_mfma_f32_16x16x32_bf16 v[108:111], v[132:135], v[214:217], v[108:111]
	v_mfma_f32_16x16x32_bf16 v[92:95], v[132:135], v[222:225], v[92:95]
	v_mfma_f32_16x16x32_bf16 v[88:91], v[158:161], v[222:225], v[88:91]
	v_mfma_f32_16x16x32_bf16 v[72:75], v[158:161], v[230:233], v[72:75]
	v_mfma_f32_16x16x32_bf16 v[76:79], v[132:135], v[230:233], v[76:79]
	v_mfma_f32_16x16x32_bf16 v[116:119], v[168:171], v[202:205], v[116:119]
	v_mfma_f32_16x16x32_bf16 v[112:115], v[176:179], v[202:205], v[112:115]
	v_mfma_f32_16x16x32_bf16 v[96:99], v[176:179], v[210:213], v[96:99]
	v_mfma_f32_16x16x32_bf16 v[100:103], v[168:171], v[210:213], v[100:103]
	v_mfma_f32_16x16x32_bf16 v[84:87], v[168:171], v[218:221], v[84:87]
	v_mfma_f32_16x16x32_bf16 v[80:83], v[176:179], v[218:221], v[80:83]
	v_mfma_f32_16x16x32_bf16 v[64:67], v[176:179], v[226:229], v[64:67]
	v_mfma_f32_16x16x32_bf16 v[68:71], v[168:171], v[226:229], v[68:71]
	v_mfma_f32_16x16x32_bf16 v[116:119], v[172:175], v[206:209], v[116:119]
	v_mfma_f32_16x16x32_bf16 v[112:115], v[194:197], v[206:209], v[112:115]
	v_mfma_f32_16x16x32_bf16 v[96:99], v[194:197], v[214:217], v[96:99]
	v_mfma_f32_16x16x32_bf16 v[100:103], v[172:175], v[214:217], v[100:103]
	v_mfma_f32_16x16x32_bf16 v[84:87], v[172:175], v[222:225], v[84:87]
	v_mfma_f32_16x16x32_bf16 v[80:83], v[194:197], v[222:225], v[80:83]
	v_mfma_f32_16x16x32_bf16 v[64:67], v[194:197], v[230:233], v[64:67]
	v_mfma_f32_16x16x32_bf16 v[68:71], v[172:175], v[230:233], v[68:71]
	s_setprio 0
	s_barrier
	s_add_i32 s0, s14, s2
	v_lshl_add_u64 v[150:151], v[150:151], 0, s[36:37]
	s_mov_b32 m0, s0
	ds_read_b128 v[202:205], v167 offset:49152
	ds_read_b128 v[206:209], v167 offset:50176
	ds_read_b128 v[210:213], v167 offset:51200
	ds_read_b128 v[214:217], v167 offset:52224
	ds_read_b128 v[218:221], v167 offset:53248
	ds_read_b128 v[222:225], v167 offset:54272
	ds_read_b128 v[226:229], v167 offset:55296
	ds_read_b128 v[230:233], v167 offset:56320
	global_load_lds_dwordx4 v[150:151], off
	v_lshl_add_u64 v[150:151], v[162:163], 0, s[36:37]
	s_add_i32 m0, s0, 0x2000
	s_add_i32 s0, s15, s2
	global_load_lds_dwordx4 v[150:151], off
	v_lshl_add_u64 v[150:151], v[180:181], 0, s[36:37]
	s_mov_b32 m0, s0
	s_nop 0
	global_load_lds_dwordx4 v[150:151], off
	v_lshl_add_u64 v[150:151], v[234:235], 0, s[36:37]
	s_add_i32 m0, s0, 0x2000
	s_nop 0
	global_load_lds_dwordx4 v[150:151], off
	v_lshl_add_u64 v[150:151], v[236:237], 0, s[36:37]
	s_mov_b32 m0, s18
	s_nop 0
	global_load_lds_dwordx4 v[150:151], off
	v_lshl_add_u64 v[150:151], v[238:239], 0, s[36:37]
	s_mov_b32 m0, s28
	s_nop 0
	global_load_lds_dwordx4 v[150:151], off
	s_waitcnt vmcnt(8)
	s_waitcnt lgkmcnt(0)
	s_barrier
	s_setprio 1
	s_waitcnt lgkmcnt(0)
	v_mfma_f32_16x16x32_bf16 v[60:63], v[128:131], v[202:205], v[60:63]
	v_mfma_f32_16x16x32_bf16 v[56:59], v[146:149], v[202:205], v[56:59]
	v_mfma_f32_16x16x32_bf16 v[40:43], v[146:149], v[210:213], v[40:43]
	v_mfma_f32_16x16x32_bf16 v[44:47], v[128:131], v[210:213], v[44:47]
	v_mfma_f32_16x16x32_bf16 v[28:31], v[128:131], v[218:221], v[28:31]
	v_mfma_f32_16x16x32_bf16 v[24:27], v[146:149], v[218:221], v[24:27]
	v_mfma_f32_16x16x32_bf16 v[8:11], v[146:149], v[226:229], v[8:11]
	v_mfma_f32_16x16x32_bf16 v[12:15], v[128:131], v[226:229], v[12:15]
	v_mfma_f32_16x16x32_bf16 v[60:63], v[132:135], v[206:209], v[60:63]
	v_mfma_f32_16x16x32_bf16 v[56:59], v[158:161], v[206:209], v[56:59]
	v_mfma_f32_16x16x32_bf16 v[40:43], v[158:161], v[214:217], v[40:43]
	v_mfma_f32_16x16x32_bf16 v[44:47], v[132:135], v[214:217], v[44:47]
	v_mfma_f32_16x16x32_bf16 v[28:31], v[132:135], v[222:225], v[28:31]
	v_mfma_f32_16x16x32_bf16 v[24:27], v[158:161], v[222:225], v[24:27]
	v_mfma_f32_16x16x32_bf16 v[8:11], v[158:161], v[230:233], v[8:11]
	v_mfma_f32_16x16x32_bf16 v[12:15], v[132:135], v[230:233], v[12:15]
	v_mfma_f32_16x16x32_bf16 v[52:55], v[168:171], v[202:205], v[52:55]
	v_mfma_f32_16x16x32_bf16 v[48:51], v[176:179], v[202:205], v[48:51]
	v_mfma_f32_16x16x32_bf16 v[32:35], v[176:179], v[210:213], v[32:35]
	v_mfma_f32_16x16x32_bf16 v[36:39], v[168:171], v[210:213], v[36:39]
	v_mfma_f32_16x16x32_bf16 v[20:23], v[168:171], v[218:221], v[20:23]
	v_mfma_f32_16x16x32_bf16 v[16:19], v[176:179], v[218:221], v[16:19]
	v_mfma_f32_16x16x32_bf16 v[0:3], v[176:179], v[226:229], v[0:3]
	v_mfma_f32_16x16x32_bf16 v[4:7], v[168:171], v[226:229], v[4:7]
	v_mfma_f32_16x16x32_bf16 v[52:55], v[172:175], v[206:209], v[52:55]
	v_mfma_f32_16x16x32_bf16 v[48:51], v[194:197], v[206:209], v[48:51]
	v_mfma_f32_16x16x32_bf16 v[32:35], v[194:197], v[214:217], v[32:35]
	v_mfma_f32_16x16x32_bf16 v[36:39], v[172:175], v[214:217], v[36:39]
	v_mfma_f32_16x16x32_bf16 v[20:23], v[172:175], v[222:225], v[20:23]
	v_mfma_f32_16x16x32_bf16 v[16:19], v[194:197], v[222:225], v[16:19]
	v_mfma_f32_16x16x32_bf16 v[0:3], v[194:197], v[230:233], v[0:3]
	v_mfma_f32_16x16x32_bf16 v[4:7], v[172:175], v[230:233], v[4:7]
	s_setprio 0
	s_barrier
	s_add_u32 s42, s42, 0x100
	s_addc_u32 s43, s43, 0
	s_add_u32 s44, s44, 0x100
	s_addc_u32 s45, s45, 0
	s_cmp_ge_u32 s47, s31
	s_mov_b32 s0, s47
	s_cbranch_scc0 .LBB0_482
	s_and_b64 vcc, exec, s[66:67]
	s_cbranch_vccz .LBB0_485
	s_barrier
